# attention work queue: next-ticket atomic returns into a dedicated VGPR and is consumed at the next loop top (vmcnt(4)), no round-trip stall at item start
# speedup vs baseline: 1.0008x; 1.0008x over previous
.LBB0_351:
	s_or_b64 exec, exec, s[0:1]
	v_mov_b32_e32 v243, v165
	s_add_u32 s44, s26, 0x1c000400
	v_mbcnt_lo_u32_b32 v0, -1, 0
	s_addc_u32 s45, s27, 0
	v_mov_b32_e32 v129, 0
	s_mov_b64 s[12:13], 0x6000000
	s_mov_b32 s46, 0x6000000
	s_movk_i32 s47, 0x90
	s_mov_b32 s48, 0x3e38aa3b
	s_mov_b32 s49, 0xc2e60000
	s_mov_b32 s50, 0xda24260
	s_movk_i32 s51, 0x81
	s_movk_i32 s52, 0x201
	s_mov_b32 s53, 0xff800000
	v_mov_b32_e32 v190, 0x42e60000
	v_mbcnt_hi_u32_b32 v191, -1, v0
	v_mov_b32_e32 v195, 0xff800000
	s_branch .LBB0_355

.LBB0_355:
	s_waitcnt vmcnt(4)
	s_and_saveexec_b64 s[0:1], s[14:15]
	ds_write_b32 v129, v243 offset:41024
	s_or_b64 exec, exec, s[0:1]
	s_waitcnt lgkmcnt(0)
	s_barrier
	ds_read_b32 v0, v129 offset:41024
	s_mov_b64 s[0:1], -1
	s_waitcnt lgkmcnt(0)
	s_barrier
	v_readfirstlane_b32 s6, v0
	s_cmpk_gt_u32 s6, 0x7ff
	s_cbranch_scc1 .LBB0_354
	s_and_saveexec_b64 s[0:1], s[14:15]
	s_cbranch_execz .LBB0_362
	v_mov_b32_e32 v1, 1
	global_atomic_add v243, v129, v1, s[10:11] sc0

	.amdhsa_kernel _Z4mega6Paramsii
		.amdhsa_group_segment_fixed_size 0
		.amdhsa_private_segment_fixed_size 0
		.amdhsa_kernarg_size 424
		.amdhsa_user_sgpr_count 2
		.amdhsa_user_sgpr_dispatch_ptr 0
		.amdhsa_user_sgpr_queue_ptr 0
		.amdhsa_user_sgpr_kernarg_segment_ptr 1
		.amdhsa_user_sgpr_dispatch_id 0
		.amdhsa_user_sgpr_kernarg_preload_length 0
		.amdhsa_user_sgpr_kernarg_preload_offset 0
		.amdhsa_user_sgpr_private_segment_size 0
		.amdhsa_uses_dynamic_stack 0
		.amdhsa_enable_private_segment 0
		.amdhsa_system_sgpr_workgroup_id_x 1
		.amdhsa_system_sgpr_workgroup_id_y 0
		.amdhsa_system_sgpr_workgroup_id_z 0
		.amdhsa_system_sgpr_workgroup_info 0
		.amdhsa_system_vgpr_workitem_id 2
		.amdhsa_next_free_vgpr 244
		.amdhsa_next_free_sgpr 101
		.amdhsa_accum_offset 244
		.amdhsa_reserve_vcc 1
		.amdhsa_float_round_mode_32 0
		.amdhsa_float_round_mode_16_64 0
		.amdhsa_float_denorm_mode_32 3
		.amdhsa_float_denorm_mode_16_64 3
		.amdhsa_dx10_clamp 1
		.amdhsa_ieee_mode 1
		.amdhsa_fp16_overflow 0
		.amdhsa_tg_split 0
		.amdhsa_exception_fp_ieee_invalid_op 0
		.amdhsa_exception_fp_denorm_src 0
		.amdhsa_exception_fp_ieee_div_zero 0
		.amdhsa_exception_fp_ieee_overflow 0
		.amdhsa_exception_fp_ieee_underflow 0
		.amdhsa_exception_fp_ieee_inexact 0
		.amdhsa_exception_int_div_zero 0
	.end_amdhsa_kernel

amdhsa.kernels:
  - .agpr_count:     0
    .args:
      - .offset:         0
        .size:           160
        .value_kind:     by_value
      - .offset:         160
        .size:           4
        .value_kind:     by_value
      - .offset:         164
        .size:           4
        .value_kind:     by_value
      - .offset:         168
        .size:           4
        .value_kind:     hidden_block_count_x
      - .offset:         172
        .size:           4
        .value_kind:     hidden_block_count_y
      - .offset:         176
        .size:           4
        .value_kind:     hidden_block_count_z
      - .offset:         180
        .size:           2
        .value_kind:     hidden_group_size_x
      - .offset:         182
        .size:           2
        .value_kind:     hidden_group_size_y
      - .offset:         184
        .size:           2
        .value_kind:     hidden_group_size_z
      - .offset:         186
        .size:           2
        .value_kind:     hidden_remainder_x
      - .offset:         188
        .size:           2
        .value_kind:     hidden_remainder_y
      - .offset:         190
        .size:           2
        .value_kind:     hidden_remainder_z
      - .offset:         208
        .size:           8
        .value_kind:     hidden_global_offset_x
      - .offset:         216
        .size:           8
        .value_kind:     hidden_global_offset_y
      - .offset:         224
        .size:           8
        .value_kind:     hidden_global_offset_z
      - .offset:         232
        .size:           2
        .value_kind:     hidden_grid_dims
      - .offset:         256
        .size:           8
        .value_kind:     hidden_multigrid_sync_arg
      - .offset:         288
        .size:           4
        .value_kind:     hidden_dynamic_lds_size
    .group_segment_fixed_size: 0
    .kernarg_segment_align: 8
    .kernarg_segment_size: 424
    .language:       OpenCL C
    .language_version:
      - 2
      - 0
    .max_flat_workgroup_size: 512
    .name:           _Z4mega6Paramsii
    .private_segment_fixed_size: 0
    .sgpr_count:     107
    .sgpr_spill_count: 3
    .symbol:         _Z4mega6Paramsii.kd
    .uniform_work_group_size: 1
    .uses_dynamic_stack: false
    .vgpr_count:     244
    .vgpr_spill_count: 0
    .wavefront_size: 64
